# MLP-up GEMM: swapped which wave half runs one barrier interval behind (waves 0-3 lag instead of waves 4-7)
# speedup vs baseline: 1.0019x; 1.0019x over previous
; template <class Epi, class Sched, bool ALIGN_EPI = false, bool SP2 = false>
; __device__ __forceinline__ void gemm_phase(PG8_LAS unsigned char* lds, const Gemm g, const Sched& S, const Epi& E, const int tid) {
;     ...
;     for (int i = 0; i < 2; ++i) { int R, C; stage_rc(tid * 16 + i * 8192, R, C); const int Rb = Epi::PERM ? (2 * (R & ~31) + perm32(R & 31)) : R;
;         voffA[i] = (unsigned)(R * K + C) * 2u; voffB[i] = (unsigned)(Rb * K + C) * 2u; }
;     const size_t kstep = (size_t)(BK * 2);
;     const size_t hstep = (size_t)HALF * K * 2;
;     const size_t tstep = 2 * hstep;
;     const size_t hstepB = Epi::PERM ? (size_t)32 * K * 2 : hstep;
;     const unsigned ldsw = (unsigned)wid * 1024u;
;     const int aoff = lds_byte(wr * 64 + fr, fq * 8), boff = lds_byte(wc * 32 + fr, fq * 8);
;     ...
;     Unit cur, nxt; int ui = 0;
;     if (!S.next(0, cur)) return;
;     f32x4 acc[2][2][4][2];
;     u32x4 iw_[Epi::HAS_INIT ? 16 : 1];
;     if constexpr (Epi::HAS_INIT) E.init_issue(iw_, cur, wr, wc, fr, fq);
;     else {
; #pragma unroll
;     for (int a = 0; a < 2; ++a)
; #pragma unroll
;         for (int b = 0; b < 2; ++b)
; #pragma unroll
;             for (int m = 0; m < 4; ++m)
; #pragma unroll
;                 for (int n = 0; n < 2; ++n) acc[a][b][m][n] = (f32x4){0.f, 0.f, 0.f, 0.f};
;     }
;     bf16x8 At[4][2], B0[2][2], B1[2][2];
;     const char* cA = (const char*)g.A + (size_t)cur.pm * tstep; const char* cB = (const char*)g.Bt + (size_t)cur.pn * tstep;
;     S.a_ready(cur);
;     if constexpr (SP2) {
;         PG8_STAGE(PG8_SB(0, 0), cB, voffB); PG8_STAGE(PG8_SB(0, 1), cB + hstepB, voffB); PG8_STAGE(PG8_SA(0, 0), cA, voffA); PG8_STAGE(PG8_SA(0, 1), cA + hstep, voffA);
;         if (wr == 1) PG8_BAR;
;         PG8_WAIT_V(2); PG8_BAR;
;         PG8_STAGE(PG8_SB(1, 0), cB + kstep, voffB); PG8_STAGE(PG8_SA(1, 0), cA + kstep, voffA); PG8_STAGE(PG8_SB(1, 1), cB + hstepB + kstep, voffB);
;         PG8_WAIT_V(6); PG8_BAR;
;     } else {
;         PG8_STAGE(PG8_SB(0, 0), cB, voffB); PG8_STAGE(PG8_SA(0, 0), cA, voffA); PG8_STAGE(PG8_SB(0, 1), cB + hstepB, voffB); PG8_STAGE(PG8_SA(0, 1), cA + hstep, voffA);
;         if (wr == 1) PG8_BAR;
;         PG8_WAIT_V(4); PG8_BAR;
;         PG8_STAGE(PG8_SB(1, 0), cB + kstep, voffB); PG8_STAGE(PG8_SA(1, 0), cA + kstep, voffA); PG8_STAGE(PG8_SB(1, 1), cB + hstepB + kstep, voffB);
;         PG8_WAIT_V(6); PG8_BAR;
.LBB0_1371:
	s_or_b64 exec, exec, s[0:1]
	v_ashrrev_i32_e32 v3, 31, v152
	v_lshrrev_b32_e32 v3, 26, v3
	v_add_u32_e32 v3, v152, v3
	v_ashrrev_i32_e32 v12, 6, v3
	v_bfe_i32 v3, v152, 27, 1
	v_lshlrev_b32_e32 v4, 4, v152
	v_lshrrev_b32_e32 v3, 22, v3
	v_add_u32_e32 v3, v4, v3
	v_and_b32_e32 v3, 0xfffffc00, v3
	v_sub_u32_e32 v3, v4, v3
	v_lshrrev_b32_e32 v5, 4, v3
	s_lshl_b64 s[0:1], s[6:7], 23
	v_bitop3_b32 v3, v5, v3, 32 bitop3:0x6c
	s_add_u32 s6, s4, s0
	v_ashrrev_i32_e32 v6, 31, v3
	s_addc_u32 s7, s5, s1
	v_lshrrev_b32_e32 v6, 26, v6
	s_add_u32 s10, s6, 0x2100000
	v_add_u32_e32 v6, v3, v6
	s_addc_u32 s11, s7, 0
	v_lshlrev_b32_e32 v5, 3, v12
	v_ashrrev_i32_e32 v13, 6, v6
	v_and_b32_e32 v6, 0xc0, v6
	s_add_u32 s6, s4, 0xc300000
	v_and_b32_e32 v5, -16, v5
	v_sub_u32_e32 v3, v3, v6
	s_addc_u32 s7, s5, 0
	v_add_u32_e32 v133, v13, v5
	v_ashrrev_i16_sdwa v3, v205, sext(v3) dst_sel:DWORD dst_unused:UNUSED_PAD src0_sel:DWORD src1_sel:BYTE_0
	s_add_u32 s4, s4, 0x17100000
	v_lshlrev_b32_e32 v5, 5, v12
	v_bfe_i32 v14, v3, 0, 16
	v_lshrrev_b32_e32 v3, 2, v133
	s_addc_u32 s5, s5, 0
	v_and_b32_e32 v5, 32, v5
	v_and_b32_e32 v154, 4, v3
	v_lshrrev_b32_e32 v3, 1, v152
	v_readfirstlane_b32 s14, v152
	v_add_u32_e32 v132, v5, v14
	v_lshlrev_b32_e32 v156, 1, v133
	v_and_b32_e32 v155, 3, v13
	v_and_b32_e32 v153, 15, v152
	s_cmpk_gt_i32 s40, 0x7f
	v_and_b32_e32 v3, 24, v3
	s_waitcnt lgkmcnt(0)
	s_barrier
	s_cbranch_scc1 .LBB0_1387
	v_add_u32_e32 v4, 0x2000, v4
	v_ashrrev_i32_e32 v5, 31, v4
	v_lshrrev_b32_e32 v5, 22, v5
	v_add_u32_e32 v5, v4, v5
	v_ashrrev_i32_e32 v15, 10, v5
	v_mul_i32_i24_e32 v5, 0x400, v15
	v_sub_u32_e32 v4, v4, v5
	v_lshrrev_b32_e32 v5, 4, v4
	v_bitop3_b32 v4, v5, v4, 32 bitop3:0x6c
	v_ashrrev_i32_e32 v5, 31, v4
	v_lshrrev_b32_e32 v5, 26, v5
	v_add_u32_e32 v5, v4, v5
	v_lshlrev_b32_e32 v6, 3, v15
	v_ashrrev_i32_e32 v16, 6, v5
	v_and_b32_e32 v6, -16, v6
	s_lshr_b32 s12, s40, 29
	v_add_u32_e32 v6, v16, v6
	s_add_i32 s12, s40, s12
	v_lshrrev_b32_e32 v7, 2, v6
	v_lshlrev_b32_e32 v9, 1, v6
	v_and_b32_e32 v5, 0xc0, v5
	s_and_b32 s13, s12, -8
	v_and_b32_e32 v7, 4, v7
	v_and_b32_e32 v8, 3, v16
	v_and_b32_e32 v9, 0x1fffd8, v9
	v_sub_u32_e32 v4, v4, v5
	s_lshl_b32 s43, s27, 3
	s_sub_i32 s13, s40, s13
	v_or3_b32 v7, v8, v7, v9
	v_lshlrev_b32_e32 v8, 5, v15
	v_ashrrev_i16_sdwa v4, v205, sext(v4) dst_sel:DWORD dst_unused:UNUSED_PAD src0_sel:DWORD src1_sel:BYTE_0
	s_add_i32 s28, s43, s13
	s_ashr_i32 s12, s12, 3
	s_ashr_i32 s15, s14, 6
	v_and_b32_e32 v8, 32, v8
	v_bfe_i32 v17, v4, 0, 16
	s_sub_i32 s34, 15, s12
	s_ashr_i32 s29, s28, 31
	s_ashr_i32 s16, s14, 8
	s_lshl_b32 s42, s15, 10
	v_add_lshl_u32 v4, v8, v17, 1
	s_lshl_b64 s[12:13], s[28:29], 19
	s_lshl_b64 s[18:19], s[34:35], 19
	v_lshl_add_u32 v134, v7, 11, v4
	v_lshl_add_u32 v136, v6, 11, v4
	v_and_b32_e32 v4, 0x1fffd8, v156
	s_lshr_b32 s85, s40, 3
	s_add_i32 s85, s85, s40
	s_and_b32 s85, s85, 3
	s_lshl_b32 s85, s85, 8
	s_add_i32 s84, s85, 0x100
	s_add_u32 s36, s10, s18
	v_or3_b32 v4, v155, v4, v154
	v_lshlrev_b32_e32 v5, 1, v132
	s_addc_u32 s37, s11, s19
	s_add_u32 s36, s36, s85
	s_addc_u32 s37, s37, 0
	s_add_i32 s29, s42, 0
	v_lshl_add_u32 v138, v4, 11, v5
	s_add_i32 m0, s29, 0x10000
	v_lshl_add_u32 v140, v133, 11, v5
	global_load_lds_dwordx4 v138, s[36:37]
	s_add_i32 m0, s29, 0x12000
	s_add_u32 s18, s36, 0x10000
	global_load_lds_dwordx4 v134, s[36:37]
	s_addc_u32 s19, s37, 0
	s_add_i32 m0, s29, 0x14000
	v_mov_b32_e32 v139, v2
	global_load_lds_dwordx4 v138, s[18:19]
	s_add_i32 m0, s29, 0x16000
	s_add_u32 s30, s6, s12
	s_addc_u32 s31, s7, s13
	s_add_u32 s30, s30, s85
	s_addc_u32 s31, s31, 0
	s_add_i32 s54, s29, 0x2000
	global_load_lds_dwordx4 v134, s[18:19]
	s_mov_b32 m0, s29
	s_add_u32 s12, s30, 0x40000
	global_load_lds_dwordx4 v140, s[30:31]
	s_mov_b32 m0, s54
	s_addc_u32 s13, s31, 0
	s_add_i32 s55, s29, 0x4000
	global_load_lds_dwordx4 v136, s[30:31]
	s_mov_b32 m0, s55
	s_add_i32 s62, s29, 0x6000
	global_load_lds_dwordx4 v140, s[12:13]
	s_mov_b32 m0, s62
	v_mov_b32_e32 v135, v2
	global_load_lds_dwordx4 v136, s[12:13]
	v_mov_b32_e32 v141, v2
	v_mov_b32_e32 v137, v2
	s_cmp_eq_u32 s16, 0
	v_lshl_add_u64 v[10:11], s[36:37], 0, v[138:139]
	v_lshl_add_u64 v[8:9], s[36:37], 0, v[134:135]
	v_lshl_add_u64 v[4:5], s[30:31], 0, v[140:141]
	s_cselect_b64 s[12:13], -1, 0
	s_cmp_lg_u32 s16, 0
	v_lshl_add_u64 v[6:7], s[30:31], 0, v[136:137]
	s_cbranch_scc1 .LBB0_1374
	s_barrier
.LBB0_1374:
	v_lshlrev_b32_e32 v18, 1, v3
	v_lshlrev_b32_e32 v19, 2, v153
	s_and_b32 s17, s15, 3
	v_lshl_or_b32 v18, v153, 6, v18
	s_lshl_b32 s15, s16, 13
	v_and_b32_e32 v20, 32, v19
	s_add_i32 m0, s29, 0x18000
	v_lshl_add_u64 v[10:11], v[10:11], 0, s[52:53]
	v_bitop3_b32 v21, v18, s15, v20 bitop3:0xde
	s_lshl_b32 s15, s17, 12
	s_waitcnt vmcnt(2)
	s_barrier
	global_load_lds_dwordx4 v[10:11], off
	v_lshl_add_u64 v[8:9], v[8:9], 0, s[52:53]
	s_add_i32 m0, s29, 0x1a000
	s_add_i32 s63, s29, 0x8000
	s_add_i32 s64, s29, 0xa000
	global_load_lds_dwordx4 v[8:9], off
	v_lshl_add_u64 v[4:5], v[4:5], 0, s[52:53]
	s_mov_b32 m0, s63
	s_add_u32 s18, s36, 0x10080
	global_load_lds_dwordx4 v[4:5], off
	v_lshl_add_u64 v[4:5], v[6:7], 0, s[52:53]
	s_mov_b32 m0, s64
	s_addc_u32 s19, s37, 0
	global_load_lds_dwordx4 v[4:5], off
	s_add_i32 m0, s29, 0x1c000
	v_lshl_add_u64 v[4:5], s[18:19], 0, v[138:139]
	global_load_lds_dwordx4 v[4:5], off
	v_lshl_add_u64 v[4:5], s[18:19], 0, v[134:135]
	s_add_i32 m0, s29, 0x1e000
	s_cmpk_gt_u32 s14, 0xff
	global_load_lds_dwordx4 v[4:5], off
	v_cmp_lt_u32_e32 vcc, 7, v153
	v_bitop3_b32 v158, s15, v18, v20 bitop3:0xf6
	s_cselect_b64 s[14:15], -1, 0
	s_lshl_b32 s17, s17, 6
	v_cndmask_b32_e64 v4, 0, 32, vcc
	v_or3_b32 v162, s17, v4, v3
	v_lshlrev_b32_e32 v4, 14, v12
	v_and_b32_e32 v4, 0xffff8000, v4
	v_lshl_add_u32 v4, v13, 11, v4
	v_and_b32_e32 v5, 1, v12
	v_lshl_or_b32 v4, v5, 6, v4
	v_lshl_add_u32 v142, v14, 1, v4
	v_lshlrev_b32_e32 v4, 14, v15
	v_lshl_or_b32 v157, s16, 6, v153
	s_lshl_b32 s16, s16, 8
	v_and_b32_e32 v4, 0xffff8000, v4
	s_waitcnt vmcnt(6)
	s_add_i32 s16, s16, 0
	v_lshl_add_u32 v4, v16, 11, v4
	v_and_b32_e32 v5, 1, v15
	s_add_i32 s16, s16, 0x20000
	v_lshl_or_b32 v4, v5, 6, v4
	s_mov_b32 s65, 0
	v_cndmask_b32_e64 v159, 0, -8, vcc
	v_cndmask_b32_e64 v160, 8, 0, vcc
	v_add_u32_e32 v161, s16, v19
	v_mov_b32_e32 v143, v2
	v_lshl_add_u32 v144, v17, 1, v4
	v_mov_b32_e32 v145, v2
	v_add_u32_e32 v163, 0, v21
	s_barrier
	s_sub_u32 s36, s36, s85
	s_subb_u32 s37, s37, 0
	s_sub_u32 s30, s30, s85
	s_subb_u32 s31, s31, 0
	s_branch .LBB0_1377
